# speedup vs baseline: 1.0188x; 1.0064x over previous
; template <class Epi>
; __device__ __forceinline__ void gemm_phase(const int tid, LAS unsigned char* lds, const Gemm g, const StaticOrder& S, const Epi& E) {
;     ...
;         const bool has_next = S.next(ui + 1, nxt);
;         const char* nA = has_next ? (const char*)g.A + (size_t)nxt.pm * tstep : cA; const char* nB = has_next ? (const char*)g.Bt + (size_t)nxt.pn * tstep : cB;
;         for (int t = 0; t < nt; t += 2) {
;             const bool last = (t == nt - 2);
;             const char* a2 = last ? nA : cA + (size_t)(t + 2) * kstep; const char* b2 = last ? nB : cB + (size_t)(t + 2) * kstep;
;             const char* a3 = a2 + kstep; const char* b3 = b2 + kstep;
;     ...
;         for (int a = 0; a < 2; ++a)
; #pragma unroll
;             for (int b = 0; b < 2; ++b)
; #pragma unroll
;                 for (int m = 0; m < 4; ++m)
; #pragma unroll
;                     for (int n = 0; n < 2; ++n) acc[a][b][m][n] = (f32x4){0.f, 0.f, 0.f, 0.f};
;         cur = nxt; cA = nA; cB = nB; ++ui;
.LBB0_335:
	v_mov_b64_e32 v[2:3], 0xae0
	s_ashr_i32 s65, s64, 31
	v_cmp_lt_i64_e32 vcc, s[24:25], v[2:3]
	s_lshl_b64 s[24:25], s[64:65], 20
	s_add_u32 s60, s62, s24
	s_addc_u32 s61, s63, s25
	s_and_b64 s[24:25], vcc, exec
	s_cselect_b32 s24, s61, s11
	s_cselect_b32 s25, s60, s10
	s_ashr_i32 s23, s22, 31
	s_lshl_b64 s[48:49], s[22:23], 20
	s_add_u32 s56, s30, s48
	s_addc_u32 s57, s36, s49
	s_and_b64 s[48:49], vcc, exec
	s_cselect_b32 s23, s57, s1
	s_cselect_b32 s27, s56, s0
	s_add_u32 s28, s10, 0x100
	s_addc_u32 s39, s11, 0
	s_add_u32 s48, s0, 0x100
	v_mov_b32_e32 v2, 0
	s_addc_u32 s49, s1, 0
	s_mov_b32 s50, -2
	v_mov_b32_e32 v3, v2
	v_mov_b64_e32 v[4:5], 0
	v_mov_b64_e32 v[6:7], 0
	v_mov_b64_e32 v[8:9], 0
	v_mov_b64_e32 v[10:11], 0
	v_mov_b64_e32 v[12:13], 0
	v_mov_b64_e32 v[14:15], 0
	v_mov_b64_e32 v[16:17], 0
	v_mov_b64_e32 v[18:19], 0
	v_mov_b64_e32 v[20:21], 0
	v_mov_b64_e32 v[22:23], 0
	v_mov_b64_e32 v[24:25], 0
	v_mov_b64_e32 v[26:27], 0
	v_mov_b64_e32 v[28:29], 0
	v_mov_b64_e32 v[30:31], 0
	v_mov_b64_e32 v[32:33], 0
	v_mov_b64_e32 v[34:35], 0
	v_mov_b64_e32 v[36:37], 0
	v_mov_b64_e32 v[38:39], 0
	v_mov_b64_e32 v[40:41], 0
	v_mov_b64_e32 v[42:43], 0
	v_mov_b64_e32 v[44:45], 0
	v_mov_b64_e32 v[46:47], 0
	v_mov_b64_e32 v[48:49], 0
	v_mov_b64_e32 v[50:51], 0
	v_mov_b64_e32 v[52:53], 0
	v_mov_b64_e32 v[54:55], 0
	v_mov_b64_e32 v[56:57], 0
	v_mov_b64_e32 v[58:59], 0
	v_mov_b64_e32 v[60:61], 0
	v_mov_b64_e32 v[62:63], 0
	v_mov_b64_e32 v[64:65], 0
	v_mov_b64_e32 v[66:67], 0
	v_mov_b64_e32 v[68:69], 0
	v_mov_b64_e32 v[70:71], 0
	v_mov_b64_e32 v[72:73], 0
	v_mov_b64_e32 v[74:75], 0
	v_mov_b64_e32 v[76:77], 0
	v_mov_b64_e32 v[78:79], 0
	v_mov_b64_e32 v[80:81], 0
	v_mov_b64_e32 v[82:83], 0
	v_mov_b64_e32 v[84:85], 0
	v_mov_b64_e32 v[86:87], 0
	v_mov_b64_e32 v[88:89], 0
	v_mov_b64_e32 v[90:91], 0
	v_mov_b64_e32 v[92:93], 0
	v_mov_b64_e32 v[94:95], 0
	v_mov_b64_e32 v[96:97], 0
	v_mov_b64_e32 v[98:99], 0
	v_mov_b64_e32 v[100:101], 0
	v_mov_b64_e32 v[102:103], 0
	v_mov_b64_e32 v[104:105], 0
	v_mov_b64_e32 v[106:107], 0
	v_mov_b64_e32 v[108:109], 0
	v_mov_b64_e32 v[110:111], 0
	v_mov_b64_e32 v[112:113], 0
	v_mov_b64_e32 v[114:115], 0
	v_mov_b64_e32 v[116:117], 0
	v_mov_b64_e32 v[118:119], 0
	v_mov_b64_e32 v[120:121], 0
	v_mov_b64_e32 v[122:123], 0
	v_mov_b64_e32 v[124:125], 0
	v_mov_b64_e32 v[126:127], 0
	v_mov_b64_e32 v[128:129], 0

; template <class Epi>
; __device__ __forceinline__ void gemm_phase(const int tid, LAS unsigned char* lds, const Gemm g, const StaticOrder& S, const Epi& E) {
;     ...
;         const bool has_next = S.next(ui + 1, nxt);
;         const char* nA = has_next ? (const char*)g.A + (size_t)nxt.pm * tstep : cA; const char* nB = has_next ? (const char*)g.Bt + (size_t)nxt.pn * tstep : cB;
;         for (int t = 0; t < nt; t += 2) {
;             const bool last = (t == nt - 2);
;             const char* a2 = last ? nA : cA + (size_t)(t + 2) * kstep; const char* b2 = last ? nB : cB + (size_t)(t + 2) * kstep;
;             const char* a3 = a2 + kstep; const char* b3 = b2 + kstep;
;     ...
;         for (int a = 0; a < 2; ++a)
; #pragma unroll
;             for (int b = 0; b < 2; ++b)
; #pragma unroll
;                 for (int m = 0; m < 4; ++m)
; #pragma unroll
;                     for (int n = 0; n < 2; ++n) acc[a][b][m][n] = (f32x4){0.f, 0.f, 0.f, 0.f};
;         cur = nxt; cA = nA; cB = nB; ++ui;
.LBB0_418:
	s_cmp_lg_u32 s12, 0
	s_cselect_b64 s[12:13], -1, 0
	s_add_u32 s60, s16, 0x100
	s_addc_u32 s61, s17, 0
	s_add_u32 s64, s14, 0x100
	v_mov_b32_e32 v2, 0
	s_mov_b32 s66, 0
	s_addc_u32 s65, s15, 0
	v_mov_b32_e32 v3, v2
	v_mov_b64_e32 v[4:5], 0
	v_mov_b64_e32 v[6:7], 0
	v_mov_b64_e32 v[8:9], 0
	v_mov_b64_e32 v[10:11], 0
	v_mov_b64_e32 v[12:13], 0
	v_mov_b64_e32 v[14:15], 0
	v_mov_b64_e32 v[16:17], 0
	v_mov_b64_e32 v[18:19], 0
	v_mov_b64_e32 v[20:21], 0
	v_mov_b64_e32 v[22:23], 0
	v_mov_b64_e32 v[24:25], 0
	v_mov_b64_e32 v[26:27], 0
	v_mov_b64_e32 v[28:29], 0
	v_mov_b64_e32 v[30:31], 0
	v_mov_b64_e32 v[32:33], 0
	v_mov_b64_e32 v[34:35], 0
	v_mov_b64_e32 v[36:37], 0
	v_mov_b64_e32 v[38:39], 0
	v_mov_b64_e32 v[40:41], 0
	v_mov_b64_e32 v[42:43], 0
	v_mov_b64_e32 v[44:45], 0
	v_mov_b64_e32 v[46:47], 0
	v_mov_b64_e32 v[48:49], 0
	v_mov_b64_e32 v[50:51], 0
	v_mov_b64_e32 v[52:53], 0
	v_mov_b64_e32 v[54:55], 0
	v_mov_b64_e32 v[56:57], 0
	v_mov_b64_e32 v[58:59], 0
	v_mov_b64_e32 v[60:61], 0
	v_mov_b64_e32 v[62:63], 0
	v_mov_b64_e32 v[64:65], 0
	v_mov_b64_e32 v[66:67], 0
	v_mov_b64_e32 v[68:69], 0
	v_mov_b64_e32 v[70:71], 0
	v_mov_b64_e32 v[72:73], 0
	v_mov_b64_e32 v[74:75], 0
	v_mov_b64_e32 v[76:77], 0
	v_mov_b64_e32 v[78:79], 0
	v_mov_b64_e32 v[80:81], 0
	v_mov_b64_e32 v[82:83], 0
	v_mov_b64_e32 v[84:85], 0
	v_mov_b64_e32 v[86:87], 0
	v_mov_b64_e32 v[88:89], 0
	v_mov_b64_e32 v[90:91], 0
	v_mov_b64_e32 v[92:93], 0
	v_mov_b64_e32 v[94:95], 0
	v_mov_b64_e32 v[96:97], 0
	v_mov_b64_e32 v[98:99], 0
	v_mov_b64_e32 v[100:101], 0
	v_mov_b64_e32 v[102:103], 0
	v_mov_b64_e32 v[104:105], 0
	v_mov_b64_e32 v[114:115], 0
	v_mov_b64_e32 v[116:117], 0
	v_mov_b64_e32 v[118:119], 0
	v_mov_b64_e32 v[120:121], 0
	v_mov_b64_e32 v[126:127], 0
	v_mov_b64_e32 v[128:129], 0
	v_mov_b64_e32 v[130:131], 0
	v_mov_b64_e32 v[132:133], 0
	v_mov_b64_e32 v[166:167], 0
	v_mov_b64_e32 v[168:169], 0
	v_mov_b64_e32 v[170:171], 0
	v_mov_b64_e32 v[172:173], 0

; template <class Epi>
; __device__ __forceinline__ void gemm_phase(const int tid, LAS unsigned char* lds, const Gemm g, const StaticOrder& S, const Epi& E) {
;     ...
;         const bool has_next = S.next(ui + 1, nxt);
;         const char* nA = has_next ? (const char*)g.A + (size_t)nxt.pm * tstep : cA; const char* nB = has_next ? (const char*)g.Bt + (size_t)nxt.pn * tstep : cB;
;         for (int t = 0; t < nt; t += 2) {
;             const bool last = (t == nt - 2);
;             const char* a2 = last ? nA : cA + (size_t)(t + 2) * kstep; const char* b2 = last ? nB : cB + (size_t)(t + 2) * kstep;
;             const char* a3 = a2 + kstep; const char* b3 = b2 + kstep;
;     ...
;         for (int a = 0; a < 2; ++a)
; #pragma unroll
;             for (int b = 0; b < 2; ++b)
; #pragma unroll
;                 for (int m = 0; m < 4; ++m)
; #pragma unroll
;                     for (int n = 0; n < 2; ++n) acc[a][b][m][n] = (f32x4){0.f, 0.f, 0.f, 0.f};
;         cur = nxt; cA = nA; cB = nB; ++ui;
.LBB0_447:
	v_mov_b64_e32 v[2:3], 0x1020
	s_ashr_i32 s13, s12, 31
	v_cmp_lt_i64_e32 vcc, s[14:15], v[2:3]
	s_lshl_b64 s[14:15], s[12:13], 20
	s_add_u32 s14, s62, s14
	s_addc_u32 s15, s63, s15
	s_and_b64 s[16:17], vcc, exec
	s_cselect_b32 s13, s15, s37
	s_cselect_b32 s57, s14, s36
	s_ashr_i32 s11, s10, 31
	s_lshl_b64 s[16:17], s[10:11], 20
	s_add_u32 s16, s26, s16
	s_addc_u32 s17, s27, s17
	s_and_b64 s[58:59], vcc, exec
	s_cselect_b32 s11, s17, s25
	s_cselect_b32 s58, s16, s24
	s_cmp_lg_u32 s22, 0
	s_cselect_b64 s[22:23], -1, 0
	s_add_u32 s59, s36, 0x100
	s_addc_u32 s60, s37, 0
	s_add_u32 s61, s24, 0x100
	v_mov_b32_e32 v2, 0
	s_addc_u32 s64, s25, 0
	s_mov_b32 s65, -2
	v_mov_b32_e32 v3, v2
	v_mov_b64_e32 v[4:5], 0
	v_mov_b64_e32 v[6:7], 0
	v_mov_b64_e32 v[8:9], 0
	v_mov_b64_e32 v[10:11], 0
	v_mov_b64_e32 v[12:13], 0
	v_mov_b64_e32 v[14:15], 0
	v_mov_b64_e32 v[16:17], 0
	v_mov_b64_e32 v[18:19], 0
	v_mov_b64_e32 v[20:21], 0
	v_mov_b64_e32 v[22:23], 0
	v_mov_b64_e32 v[24:25], 0
	v_mov_b64_e32 v[26:27], 0
	v_mov_b64_e32 v[28:29], 0
	v_mov_b64_e32 v[30:31], 0
	v_mov_b64_e32 v[32:33], 0
	v_mov_b64_e32 v[34:35], 0
	v_mov_b64_e32 v[36:37], 0
	v_mov_b64_e32 v[38:39], 0
	v_mov_b64_e32 v[40:41], 0
	v_mov_b64_e32 v[42:43], 0
	v_mov_b64_e32 v[44:45], 0
	v_mov_b64_e32 v[46:47], 0
	v_mov_b64_e32 v[48:49], 0
	v_mov_b64_e32 v[50:51], 0
	v_mov_b64_e32 v[52:53], 0
	v_mov_b64_e32 v[54:55], 0
	v_mov_b64_e32 v[56:57], 0
	v_mov_b64_e32 v[58:59], 0
	v_mov_b64_e32 v[60:61], 0
	v_mov_b64_e32 v[62:63], 0
	v_mov_b64_e32 v[64:65], 0
	v_mov_b64_e32 v[66:67], 0
	v_mov_b64_e32 v[68:69], 0
	v_mov_b64_e32 v[70:71], 0
	v_mov_b64_e32 v[72:73], 0
	v_mov_b64_e32 v[74:75], 0
	v_mov_b64_e32 v[76:77], 0
	v_mov_b64_e32 v[78:79], 0
	v_mov_b64_e32 v[80:81], 0
	v_mov_b64_e32 v[82:83], 0
	v_mov_b64_e32 v[84:85], 0
	v_mov_b64_e32 v[86:87], 0
	v_mov_b64_e32 v[88:89], 0
	v_mov_b64_e32 v[90:91], 0
	v_mov_b64_e32 v[92:93], 0
	v_mov_b64_e32 v[94:95], 0
	v_mov_b64_e32 v[96:97], 0
	v_mov_b64_e32 v[98:99], 0
	v_mov_b64_e32 v[100:101], 0
	v_mov_b64_e32 v[102:103], 0
	v_mov_b64_e32 v[104:105], 0
	v_mov_b64_e32 v[106:107], 0
	v_mov_b64_e32 v[108:109], 0
	v_mov_b64_e32 v[110:111], 0
	v_mov_b64_e32 v[112:113], 0
	v_mov_b64_e32 v[114:115], 0
	v_mov_b64_e32 v[116:117], 0
	v_mov_b64_e32 v[118:119], 0
	v_mov_b64_e32 v[120:121], 0
	v_mov_b64_e32 v[122:123], 0
	v_mov_b64_e32 v[124:125], 0
	v_mov_b64_e32 v[126:127], 0
	v_mov_b64_e32 v[128:129], 0
